# pool mixer: window loads issued together instead of one load per wait
# speedup vs baseline: 1.0046x; 1.0046x over previous
.LBB0_465:
	v_mov_b32_e32 v88, 0
	v_mov_b64_e32 v[92:93], v[78:79]
	v_mov_b32_e32 v89, v88
	v_mov_b32_e32 v84, v88
	v_mov_b32_e32 v85, v88
	v_mov_b32_e32 v90, v88
	v_mov_b32_e32 v91, v88
	v_mov_b32_e32 v86, v88
	v_mov_b32_e32 v87, v88
	s_mov_b64 s[10:11], exec
	v_cmp_le_u32_e32 vcc, 0, v95
	s_and_b64 exec, exec, vcc
	global_load_dwordx4 v[120:123], v[92:93], off
	v_lshl_add_u64 v[92:93], v[92:93], 0, s[4:5]
	v_cmp_le_u32_e32 vcc, 1, v95
	s_and_b64 exec, exec, vcc
	global_load_dwordx4 v[124:127], v[92:93], off
	v_lshl_add_u64 v[92:93], v[92:93], 0, s[4:5]
	s_cmp_eq_u32 s12, 2
	s_cbranch_scc1 .Lmy_pool_issued
	v_cmp_le_u32_e32 vcc, 2, v95
	s_and_b64 exec, exec, vcc
	global_load_dwordx4 v[128:131], v[92:93], off
	v_lshl_add_u64 v[92:93], v[92:93], 0, s[4:5]
	v_cmp_le_u32_e32 vcc, 3, v95
	s_and_b64 exec, exec, vcc
	global_load_dwordx4 v[132:135], v[92:93], off
	v_lshl_add_u64 v[92:93], v[92:93], 0, s[4:5]
	s_cmp_eq_u32 s12, 4
	s_cbranch_scc1 .Lmy_pool_issued
	v_cmp_le_u32_e32 vcc, 4, v95
	s_and_b64 exec, exec, vcc
	global_load_dwordx4 v[136:139], v[92:93], off
	v_lshl_add_u64 v[92:93], v[92:93], 0, s[4:5]
	v_cmp_le_u32_e32 vcc, 5, v95
	s_and_b64 exec, exec, vcc
	global_load_dwordx4 v[140:143], v[92:93], off
	v_lshl_add_u64 v[92:93], v[92:93], 0, s[4:5]
	v_cmp_le_u32_e32 vcc, 6, v95
	s_and_b64 exec, exec, vcc
	global_load_dwordx4 v[144:147], v[92:93], off
	v_lshl_add_u64 v[92:93], v[92:93], 0, s[4:5]
	v_cmp_le_u32_e32 vcc, 7, v95
	s_and_b64 exec, exec, vcc
	global_load_dwordx4 v[148:151], v[92:93], off
	v_lshl_add_u64 v[92:93], v[92:93], 0, s[4:5]
	s_cmp_eq_u32 s12, 8
	s_cbranch_scc1 .Lmy_pool_issued
	v_cmp_le_u32_e32 vcc, 8, v95
	s_and_b64 exec, exec, vcc
	global_load_dwordx4 v[152:155], v[92:93], off
	v_lshl_add_u64 v[92:93], v[92:93], 0, s[4:5]
	v_cmp_le_u32_e32 vcc, 9, v95
	s_and_b64 exec, exec, vcc
	global_load_dwordx4 v[156:159], v[92:93], off
	v_lshl_add_u64 v[92:93], v[92:93], 0, s[4:5]
	v_cmp_le_u32_e32 vcc, 10, v95
	s_and_b64 exec, exec, vcc
	global_load_dwordx4 v[160:163], v[92:93], off
	v_lshl_add_u64 v[92:93], v[92:93], 0, s[4:5]
	v_cmp_le_u32_e32 vcc, 11, v95
	s_and_b64 exec, exec, vcc
	global_load_dwordx4 v[164:167], v[92:93], off
	v_lshl_add_u64 v[92:93], v[92:93], 0, s[4:5]
	v_cmp_le_u32_e32 vcc, 12, v95
	s_and_b64 exec, exec, vcc
	global_load_dwordx4 v[168:171], v[92:93], off
	v_lshl_add_u64 v[92:93], v[92:93], 0, s[4:5]
	v_cmp_le_u32_e32 vcc, 13, v95
	s_and_b64 exec, exec, vcc
	global_load_dwordx4 v[172:175], v[92:93], off
	v_lshl_add_u64 v[92:93], v[92:93], 0, s[4:5]
	v_cmp_le_u32_e32 vcc, 14, v95
	s_and_b64 exec, exec, vcc
	global_load_dwordx4 v[176:179], v[92:93], off
	v_lshl_add_u64 v[92:93], v[92:93], 0, s[4:5]
	v_cmp_le_u32_e32 vcc, 15, v95
	s_and_b64 exec, exec, vcc
	global_load_dwordx4 v[180:183], v[92:93], off
	v_lshl_add_u64 v[92:93], v[92:93], 0, s[4:5]
.Lmy_pool_issued:
	s_mov_b64 exec, s[10:11]
	s_waitcnt vmcnt(0)
	v_cmp_le_u32_e32 vcc, 0, v95
	s_and_b64 exec, exec, vcc
	v_lshlrev_b32_e32 v100, 16, v120
	v_and_b32_e32 v101, 0xffff0000, v120
	v_lshlrev_b32_e32 v96, 16, v121
	v_and_b32_e32 v97, 0xffff0000, v121
	v_lshlrev_b32_e32 v102, 16, v122
	v_and_b32_e32 v103, 0xffff0000, v122
	v_lshlrev_b32_e32 v98, 16, v123
	v_and_b32_e32 v99, 0xffff0000, v123
	v_pk_add_f32 v[88:89], v[88:89], v[100:101]
	v_pk_add_f32 v[84:85], v[84:85], v[96:97]
	v_pk_add_f32 v[90:91], v[90:91], v[102:103]
	v_pk_add_f32 v[86:87], v[86:87], v[98:99]
	v_cmp_le_u32_e32 vcc, 1, v95
	s_and_b64 exec, exec, vcc
	v_lshlrev_b32_e32 v100, 16, v124
	v_and_b32_e32 v101, 0xffff0000, v124
	v_lshlrev_b32_e32 v96, 16, v125
	v_and_b32_e32 v97, 0xffff0000, v125
	v_lshlrev_b32_e32 v102, 16, v126
	v_and_b32_e32 v103, 0xffff0000, v126
	v_lshlrev_b32_e32 v98, 16, v127
	v_and_b32_e32 v99, 0xffff0000, v127
	v_pk_add_f32 v[88:89], v[88:89], v[100:101]
	v_pk_add_f32 v[84:85], v[84:85], v[96:97]
	v_pk_add_f32 v[90:91], v[90:91], v[102:103]
	v_pk_add_f32 v[86:87], v[86:87], v[98:99]
	s_cmp_eq_u32 s12, 2
	s_cbranch_scc1 .Lmy_pool_acc_done
	v_cmp_le_u32_e32 vcc, 2, v95
	s_and_b64 exec, exec, vcc
	v_lshlrev_b32_e32 v100, 16, v128
	v_and_b32_e32 v101, 0xffff0000, v128
	v_lshlrev_b32_e32 v96, 16, v129
	v_and_b32_e32 v97, 0xffff0000, v129
	v_lshlrev_b32_e32 v102, 16, v130
	v_and_b32_e32 v103, 0xffff0000, v130
	v_lshlrev_b32_e32 v98, 16, v131
	v_and_b32_e32 v99, 0xffff0000, v131
	v_pk_add_f32 v[88:89], v[88:89], v[100:101]
	v_pk_add_f32 v[84:85], v[84:85], v[96:97]
	v_pk_add_f32 v[90:91], v[90:91], v[102:103]
	v_pk_add_f32 v[86:87], v[86:87], v[98:99]
	v_cmp_le_u32_e32 vcc, 3, v95
	s_and_b64 exec, exec, vcc
	v_lshlrev_b32_e32 v100, 16, v132
	v_and_b32_e32 v101, 0xffff0000, v132
	v_lshlrev_b32_e32 v96, 16, v133
	v_and_b32_e32 v97, 0xffff0000, v133
	v_lshlrev_b32_e32 v102, 16, v134
	v_and_b32_e32 v103, 0xffff0000, v134
	v_lshlrev_b32_e32 v98, 16, v135
	v_and_b32_e32 v99, 0xffff0000, v135
	v_pk_add_f32 v[88:89], v[88:89], v[100:101]
	v_pk_add_f32 v[84:85], v[84:85], v[96:97]
	v_pk_add_f32 v[90:91], v[90:91], v[102:103]
	v_pk_add_f32 v[86:87], v[86:87], v[98:99]
	s_cmp_eq_u32 s12, 4
	s_cbranch_scc1 .Lmy_pool_acc_done
	v_cmp_le_u32_e32 vcc, 4, v95
	s_and_b64 exec, exec, vcc
	v_lshlrev_b32_e32 v100, 16, v136
	v_and_b32_e32 v101, 0xffff0000, v136
	v_lshlrev_b32_e32 v96, 16, v137
	v_and_b32_e32 v97, 0xffff0000, v137
	v_lshlrev_b32_e32 v102, 16, v138
	v_and_b32_e32 v103, 0xffff0000, v138
	v_lshlrev_b32_e32 v98, 16, v139
	v_and_b32_e32 v99, 0xffff0000, v139
	v_pk_add_f32 v[88:89], v[88:89], v[100:101]
	v_pk_add_f32 v[84:85], v[84:85], v[96:97]
	v_pk_add_f32 v[90:91], v[90:91], v[102:103]
	v_pk_add_f32 v[86:87], v[86:87], v[98:99]
	v_cmp_le_u32_e32 vcc, 5, v95
	s_and_b64 exec, exec, vcc
	v_lshlrev_b32_e32 v100, 16, v140
	v_and_b32_e32 v101, 0xffff0000, v140
	v_lshlrev_b32_e32 v96, 16, v141
	v_and_b32_e32 v97, 0xffff0000, v141
	v_lshlrev_b32_e32 v102, 16, v142
	v_and_b32_e32 v103, 0xffff0000, v142
	v_lshlrev_b32_e32 v98, 16, v143
	v_and_b32_e32 v99, 0xffff0000, v143
	v_pk_add_f32 v[88:89], v[88:89], v[100:101]
	v_pk_add_f32 v[84:85], v[84:85], v[96:97]
	v_pk_add_f32 v[90:91], v[90:91], v[102:103]
	v_pk_add_f32 v[86:87], v[86:87], v[98:99]
	v_cmp_le_u32_e32 vcc, 6, v95
	s_and_b64 exec, exec, vcc
	v_lshlrev_b32_e32 v100, 16, v144
	v_and_b32_e32 v101, 0xffff0000, v144
	v_lshlrev_b32_e32 v96, 16, v145
	v_and_b32_e32 v97, 0xffff0000, v145
	v_lshlrev_b32_e32 v102, 16, v146
	v_and_b32_e32 v103, 0xffff0000, v146
	v_lshlrev_b32_e32 v98, 16, v147
	v_and_b32_e32 v99, 0xffff0000, v147
	v_pk_add_f32 v[88:89], v[88:89], v[100:101]
	v_pk_add_f32 v[84:85], v[84:85], v[96:97]
	v_pk_add_f32 v[90:91], v[90:91], v[102:103]
	v_pk_add_f32 v[86:87], v[86:87], v[98:99]
	v_cmp_le_u32_e32 vcc, 7, v95
	s_and_b64 exec, exec, vcc
	v_lshlrev_b32_e32 v100, 16, v148
	v_and_b32_e32 v101, 0xffff0000, v148
	v_lshlrev_b32_e32 v96, 16, v149
	v_and_b32_e32 v97, 0xffff0000, v149
	v_lshlrev_b32_e32 v102, 16, v150
	v_and_b32_e32 v103, 0xffff0000, v150
	v_lshlrev_b32_e32 v98, 16, v151
	v_and_b32_e32 v99, 0xffff0000, v151
	v_pk_add_f32 v[88:89], v[88:89], v[100:101]
	v_pk_add_f32 v[84:85], v[84:85], v[96:97]
	v_pk_add_f32 v[90:91], v[90:91], v[102:103]
	v_pk_add_f32 v[86:87], v[86:87], v[98:99]
	s_cmp_eq_u32 s12, 8
	s_cbranch_scc1 .Lmy_pool_acc_done
	v_cmp_le_u32_e32 vcc, 8, v95
	s_and_b64 exec, exec, vcc
	v_lshlrev_b32_e32 v100, 16, v152
	v_and_b32_e32 v101, 0xffff0000, v152
	v_lshlrev_b32_e32 v96, 16, v153
	v_and_b32_e32 v97, 0xffff0000, v153
	v_lshlrev_b32_e32 v102, 16, v154
	v_and_b32_e32 v103, 0xffff0000, v154
	v_lshlrev_b32_e32 v98, 16, v155
	v_and_b32_e32 v99, 0xffff0000, v155
	v_pk_add_f32 v[88:89], v[88:89], v[100:101]
	v_pk_add_f32 v[84:85], v[84:85], v[96:97]
	v_pk_add_f32 v[90:91], v[90:91], v[102:103]
	v_pk_add_f32 v[86:87], v[86:87], v[98:99]
	v_cmp_le_u32_e32 vcc, 9, v95
	s_and_b64 exec, exec, vcc
	v_lshlrev_b32_e32 v100, 16, v156
	v_and_b32_e32 v101, 0xffff0000, v156
	v_lshlrev_b32_e32 v96, 16, v157
	v_and_b32_e32 v97, 0xffff0000, v157
	v_lshlrev_b32_e32 v102, 16, v158
	v_and_b32_e32 v103, 0xffff0000, v158
	v_lshlrev_b32_e32 v98, 16, v159
	v_and_b32_e32 v99, 0xffff0000, v159
	v_pk_add_f32 v[88:89], v[88:89], v[100:101]
	v_pk_add_f32 v[84:85], v[84:85], v[96:97]
	v_pk_add_f32 v[90:91], v[90:91], v[102:103]
	v_pk_add_f32 v[86:87], v[86:87], v[98:99]
	v_cmp_le_u32_e32 vcc, 10, v95
	s_and_b64 exec, exec, vcc
	v_lshlrev_b32_e32 v100, 16, v160
	v_and_b32_e32 v101, 0xffff0000, v160
	v_lshlrev_b32_e32 v96, 16, v161
	v_and_b32_e32 v97, 0xffff0000, v161
	v_lshlrev_b32_e32 v102, 16, v162
	v_and_b32_e32 v103, 0xffff0000, v162
	v_lshlrev_b32_e32 v98, 16, v163
	v_and_b32_e32 v99, 0xffff0000, v163
	v_pk_add_f32 v[88:89], v[88:89], v[100:101]
	v_pk_add_f32 v[84:85], v[84:85], v[96:97]
	v_pk_add_f32 v[90:91], v[90:91], v[102:103]
	v_pk_add_f32 v[86:87], v[86:87], v[98:99]
	v_cmp_le_u32_e32 vcc, 11, v95
	s_and_b64 exec, exec, vcc
	v_lshlrev_b32_e32 v100, 16, v164
	v_and_b32_e32 v101, 0xffff0000, v164
	v_lshlrev_b32_e32 v96, 16, v165
	v_and_b32_e32 v97, 0xffff0000, v165
	v_lshlrev_b32_e32 v102, 16, v166
	v_and_b32_e32 v103, 0xffff0000, v166
	v_lshlrev_b32_e32 v98, 16, v167
	v_and_b32_e32 v99, 0xffff0000, v167
	v_pk_add_f32 v[88:89], v[88:89], v[100:101]
	v_pk_add_f32 v[84:85], v[84:85], v[96:97]
	v_pk_add_f32 v[90:91], v[90:91], v[102:103]
	v_pk_add_f32 v[86:87], v[86:87], v[98:99]
	v_cmp_le_u32_e32 vcc, 12, v95
	s_and_b64 exec, exec, vcc
	v_lshlrev_b32_e32 v100, 16, v168
	v_and_b32_e32 v101, 0xffff0000, v168
	v_lshlrev_b32_e32 v96, 16, v169
	v_and_b32_e32 v97, 0xffff0000, v169
	v_lshlrev_b32_e32 v102, 16, v170
	v_and_b32_e32 v103, 0xffff0000, v170
	v_lshlrev_b32_e32 v98, 16, v171
	v_and_b32_e32 v99, 0xffff0000, v171
	v_pk_add_f32 v[88:89], v[88:89], v[100:101]
	v_pk_add_f32 v[84:85], v[84:85], v[96:97]
	v_pk_add_f32 v[90:91], v[90:91], v[102:103]
	v_pk_add_f32 v[86:87], v[86:87], v[98:99]
	v_cmp_le_u32_e32 vcc, 13, v95
	s_and_b64 exec, exec, vcc
	v_lshlrev_b32_e32 v100, 16, v172
	v_and_b32_e32 v101, 0xffff0000, v172
	v_lshlrev_b32_e32 v96, 16, v173
	v_and_b32_e32 v97, 0xffff0000, v173
	v_lshlrev_b32_e32 v102, 16, v174
	v_and_b32_e32 v103, 0xffff0000, v174
	v_lshlrev_b32_e32 v98, 16, v175
	v_and_b32_e32 v99, 0xffff0000, v175
	v_pk_add_f32 v[88:89], v[88:89], v[100:101]
	v_pk_add_f32 v[84:85], v[84:85], v[96:97]
	v_pk_add_f32 v[90:91], v[90:91], v[102:103]
	v_pk_add_f32 v[86:87], v[86:87], v[98:99]
	v_cmp_le_u32_e32 vcc, 14, v95
	s_and_b64 exec, exec, vcc
	v_lshlrev_b32_e32 v100, 16, v176
	v_and_b32_e32 v101, 0xffff0000, v176
	v_lshlrev_b32_e32 v96, 16, v177
	v_and_b32_e32 v97, 0xffff0000, v177
	v_lshlrev_b32_e32 v102, 16, v178
	v_and_b32_e32 v103, 0xffff0000, v178
	v_lshlrev_b32_e32 v98, 16, v179
	v_and_b32_e32 v99, 0xffff0000, v179
	v_pk_add_f32 v[88:89], v[88:89], v[100:101]
	v_pk_add_f32 v[84:85], v[84:85], v[96:97]
	v_pk_add_f32 v[90:91], v[90:91], v[102:103]
	v_pk_add_f32 v[86:87], v[86:87], v[98:99]
	v_cmp_le_u32_e32 vcc, 15, v95
	s_and_b64 exec, exec, vcc
	v_lshlrev_b32_e32 v100, 16, v180
	v_and_b32_e32 v101, 0xffff0000, v180
	v_lshlrev_b32_e32 v96, 16, v181
	v_and_b32_e32 v97, 0xffff0000, v181
	v_lshlrev_b32_e32 v102, 16, v182
	v_and_b32_e32 v103, 0xffff0000, v182
	v_lshlrev_b32_e32 v98, 16, v183
	v_and_b32_e32 v99, 0xffff0000, v183
	v_pk_add_f32 v[88:89], v[88:89], v[100:101]
	v_pk_add_f32 v[84:85], v[84:85], v[96:97]
	v_pk_add_f32 v[90:91], v[90:91], v[102:103]
	v_pk_add_f32 v[86:87], v[86:87], v[98:99]
.Lmy_pool_acc_done:
	s_mov_b64 exec, s[10:11]
	s_branch .LBB0_464
